# DK32 latent attention inner loop restructured: Q frags in VGPRs, mid-iteration barrier with K-frag prefetch, permlane32 row max, full-iteration global prefetch
# speedup vs baseline: 1.0137x; 1.0137x over previous
; template <int DK>
; DI void attn_item(const Params& p, int layer, int b, int hd, int qt, int ctxq, char* smem) {
;     ...
;     for (int kt = 0; kt < nkt; ++kt) {
;         const int cur = kt & 1;
;         const bf16_t* kb_ = sK + cur * 64 * 72; const bf16_t* vb_ = sV + cur * 64 * 68;
; #pragma unroll
;         for (int s = 0; s < 2; ++s) {
;             if (s == 1) {
;                 if (kt + 1 < nkt) {
; #pragma unroll
;                     for (int i = 0; i < 2; ++i) { rk[i] = *(const u32x4*)(Kg + (size_t)((kt + 1) * 64 + srow + 32 * i) * 64 + sc8); rv[i] = *(const u32x4*)(Vg + (size_t)(srow + 32 * i) * NKEY + (kt + 1) * 64 + sc8); }
;                 }
;             }
;             f32x16 x[2];
; #pragma unroll
;             for (int kb = 0; kb < 2; ++kb)
; #pragma unroll
;                 for (int i = 0; i < 16; ++i) x[kb][i] = 0.f;
;             const int kofs = DK == 32 ? 32 * s : 0;
; #pragma unroll
;             for (int ks = 0; ks < NKS; ++ks) {
;                 const bf16x8 a0 = *(const bf16x8*)(kb_ + r * 72 + kofs + 16 * ks + 8 * h), a1 = *(const bf16x8*)(kb_ + (32 + r) * 72 + kofs + 16 * ks + 8 * h);
;                 const bf16x8 qv = *(const bf16x8*)(sQ + ((s * NKS + ks) * 64 + lane) * 8);
;                 x[0] = MFMA32(a0, qv, x[0]); x[1] = MFMA32(a1, qv, x[1]);
;             }
;             float mx = x[0][0];
; #pragma unroll
;             for (int i = 1; i < 16; ++i) mx = fmaxf(mx, x[0][i]);
; #pragma unroll
;             for (int i = 0; i < 16; ++i) mx = fmaxf(mx, x[1][i]);
;             mx = fmaxf(mx, shx(mx, lane, 32));
;             if (__builtin_amdgcn_ballot_w64(mx > m_[s] + 8.f) != 0) {
;                 const float mn = fmaxf(m_[s], mx);
;                 const float al = __builtin_amdgcn_exp2f(m_[s] - mn);
;                 m_[s] = mn;
;                 l_[s] *= al;
; #pragma unroll
;                 for (int d = 0; d < 2; ++d)
; #pragma unroll
;                     for (int i = 0; i < 16; ++i) O[s][d][i] *= al;
;             }
;             const f32x2 mref = {m_[s], m_[s]};
;             float ps = 0.f;
; #pragma unroll
;             for (int kb = 0; kb < 2; ++kb)
; #pragma unroll
;                 for (int i2 = 0; i2 < 8; ++i2) {
;                     f32x2 t = {x[kb][2 * i2], x[kb][2 * i2 + 1]};
;                     asm("v_pk_add_f32 %0, %1, %2 neg_lo:[0,1] neg_hi:[0,1]" : "=v"(t) : "v"(t), "v"(mref));
.LBB0_158:
	s_mov_b32 s8, 0
	ds_read_b128 v[216:219], v171 offset:35840
	ds_read_b128 v[220:223], v171 offset:36864
	ds_read_b128 v[224:227], v171 offset:37888
	ds_read_b128 v[240:243], v171 offset:38912
	ds_read_b128 v[128:131], v149
	ds_read_b128 v[132:135], v149 offset:4608
	ds_read_b128 v[136:139], v149 offset:32
	ds_read_b128 v[140:143], v149 offset:4640
	v_lshl_add_u64 v[244:245], v[154:155], 0, v[160:161]
	s_mov_b64 s[10:11], 0x84000
	v_lshl_add_u64 v[246:247], v[244:245], 0, s[10:11]
	v_lshl_add_u64 v[248:249], v[156:157], 0, v[160:161]
	s_mov_b64 s[10:11], 0x3000
	v_lshl_add_u64 v[248:249], v[248:249], 0, s[10:11]
	global_load_dwordx4 v[190:193], v[248:249], off offset:-4096
	global_load_dwordx4 v[194:197], v[248:249], off
	global_load_dwordx4 v[198:201], v[244:245], off offset:128
	global_load_dwordx4 v[202:205], v[246:247], off offset:128
	v_mov_b32_e32 v153, v152
	v_mov_b32_e32 v147, v146
.Lat32_loop:
	s_and_b32 s9, s8, 1
	s_mul_i32 s10, s9, 0x2400
	s_mul_i32 s11, s9, 0x2200
	v_add_u32_e32 v206, s10, v149
	v_add_u32_e32 v207, s11, v172
	v_add_u32_e32 v208, 0x5800, v207
	v_add_u32_e32 v207, 0x4800, v207
	s_waitcnt lgkmcnt(0)
	v_mfma_f32_32x32x16_bf16 v[80:95], v[128:131], v[216:219], 0
	v_mfma_f32_32x32x16_bf16 v[80:95], v[136:139], v[220:223], v[80:95]
	v_mfma_f32_32x32x16_bf16 v[64:79], v[132:135], v[216:219], 0
	v_mfma_f32_32x32x16_bf16 v[64:79], v[140:143], v[220:223], v[64:79]
	ds_read2_b64 v[96:99], v207 offset0:0 offset1:2
	ds_read2_b64 v[112:115], v208 offset0:32 offset1:34
	ds_read2_b64 v[100:103], v207 offset0:4 offset1:6
	ds_read2_b64 v[116:119], v208 offset0:36 offset1:38
	ds_read2_b64 v[104:107], v207 offset0:8 offset1:10
	ds_read2_b64 v[120:123], v208 offset0:40 offset1:42
	ds_read2_b64 v[108:111], v207 offset0:12 offset1:14
	ds_read2_b64 v[124:127], v208 offset0:44 offset1:46
	ds_read_b128 v[174:177], v206 offset:64
	ds_read_b128 v[178:181], v206 offset:4672
	ds_read_b128 v[182:185], v206 offset:96
	ds_read_b128 v[186:189], v206 offset:4704
	v_max3_f32 v209, v80, v81, v82
	v_max3_f32 v209, v209, v83, v84
	v_max3_f32 v209, v209, v85, v86
	v_max3_f32 v209, v209, v87, v88
	v_max3_f32 v209, v209, v89, v90
	v_max3_f32 v209, v209, v91, v92
	v_max3_f32 v209, v209, v93, v94
	v_max3_f32 v209, v209, v95, v64
	v_max3_f32 v209, v209, v65, v66
	v_max3_f32 v209, v209, v67, v68
	v_max3_f32 v209, v209, v69, v70
	v_max3_f32 v209, v209, v71, v72
	v_max3_f32 v209, v209, v73, v74
	v_max3_f32 v209, v209, v75, v76
	v_max3_f32 v209, v209, v77, v78
	v_max_f32_e32 v209, v209, v79
	v_mov_b32_e32 v210, v209
	s_nop 1
	v_permlane32_swap_b32_e32 v210, v209
	s_nop 0
	v_max_f32_e32 v209, v209, v210
	v_add_f32_e32 v210, 0x41000000, v152
	v_cmp_gt_f32_e32 vcc, v209, v210
	s_cbranch_vccz .Lat32_nors0
	v_max_f32_e32 v213, v152, v209
	v_sub_f32_e32 v210, v152, v213
	v_exp_f32_e32 v210, v210
	v_mov_b32_e32 v152, v213
	v_mov_b32_e32 v153, v213
	v_mul_f32_e32 v151, v151, v210
	v_pk_mul_f32 v[32:33], v[32:33], v[210:211] op_sel_hi:[1,0]
	v_pk_mul_f32 v[34:35], v[34:35], v[210:211] op_sel_hi:[1,0]
	v_pk_mul_f32 v[36:37], v[36:37], v[210:211] op_sel_hi:[1,0]
	v_pk_mul_f32 v[38:39], v[38:39], v[210:211] op_sel_hi:[1,0]
	v_pk_mul_f32 v[40:41], v[40:41], v[210:211] op_sel_hi:[1,0]
	v_pk_mul_f32 v[42:43], v[42:43], v[210:211] op_sel_hi:[1,0]
	v_pk_mul_f32 v[44:45], v[44:45], v[210:211] op_sel_hi:[1,0]
	v_pk_mul_f32 v[46:47], v[46:47], v[210:211] op_sel_hi:[1,0]
	v_pk_mul_f32 v[0:1], v[0:1], v[210:211] op_sel_hi:[1,0]
	v_pk_mul_f32 v[2:3], v[2:3], v[210:211] op_sel_hi:[1,0]
	v_pk_mul_f32 v[4:5], v[4:5], v[210:211] op_sel_hi:[1,0]
	v_pk_mul_f32 v[6:7], v[6:7], v[210:211] op_sel_hi:[1,0]
	v_pk_mul_f32 v[8:9], v[8:9], v[210:211] op_sel_hi:[1,0]
	v_pk_mul_f32 v[10:11], v[10:11], v[210:211] op_sel_hi:[1,0]
	v_pk_mul_f32 v[12:13], v[12:13], v[210:211] op_sel_hi:[1,0]
	v_pk_mul_f32 v[14:15], v[14:15], v[210:211] op_sel_hi:[1,0]
.Lat32_nors0:
	v_pk_add_f32 v[80:81], v[80:81], v[152:153] neg_lo:[0,1] neg_hi:[0,1]
	v_pk_add_f32 v[82:83], v[82:83], v[152:153] neg_lo:[0,1] neg_hi:[0,1]
	v_pk_add_f32 v[84:85], v[84:85], v[152:153] neg_lo:[0,1] neg_hi:[0,1]
	v_pk_add_f32 v[86:87], v[86:87], v[152:153] neg_lo:[0,1] neg_hi:[0,1]
	v_exp_f32_e32 v80, v80
	v_exp_f32_e32 v81, v81
	v_exp_f32_e32 v82, v82
	v_exp_f32_e32 v83, v83
	v_exp_f32_e32 v84, v84
	v_exp_f32_e32 v85, v85
	v_exp_f32_e32 v86, v86
	v_exp_f32_e32 v87, v87
	v_add_f32_e32 v211, v80, v82
	v_add_f32_e32 v212, v81, v83
	v_add_f32_e32 v211, v211, v84
	v_add_f32_e32 v212, v212, v85
	v_add_f32_e32 v211, v211, v86
	v_add_f32_e32 v212, v212, v87
	v_cvt_pk_bf16_f32 v80, v80, v81
	v_cvt_pk_bf16_f32 v81, v82, v83
	v_cvt_pk_bf16_f32 v82, v84, v85
	v_cvt_pk_bf16_f32 v83, v86, v87
	s_waitcnt lgkmcnt(0)
; #define MFMA32(a, b, c) __builtin_amdgcn_mfma_f32_32x32x16_bf16((a), (b), (c), 0, 0, 0)
; DI unsigned pk_bf16(float a, float b) { f32x2 v = {a, b}; bf16v2 r = __builtin_convertvector(v, bf16v2); return __builtin_bit_cast(unsigned, r); }
; template <int DK>
; DI void attn_item(const Params& p, int layer, int b, int hd, int qt, int ctxq, char* smem) {
;     ...
;             const f32x2 mref = {m_[s], m_[s]};
;             float ps = 0.f;
; #pragma unroll
;             for (int kb = 0; kb < 2; ++kb)
; #pragma unroll
;                 for (int i2 = 0; i2 < 8; ++i2) {
;                     f32x2 t = {x[kb][2 * i2], x[kb][2 * i2 + 1]};
;                     asm("v_pk_add_f32 %0, %1, %2 neg_lo:[0,1] neg_hi:[0,1]" : "=v"(t) : "v"(t), "v"(mref));
;                     const float e0 = __builtin_amdgcn_exp2f(t.x), e1 = __builtin_amdgcn_exp2f(t.y);
;                     x[kb][2 * i2] = e0; x[kb][2 * i2 + 1] = e1; ps += e0 + e1;
;                 }
;             l_[s] += ps;
; #pragma unroll
;             for (int kb = 0; kb < 2; ++kb)
; #pragma unroll
;                 for (int st = 0; st < 2; ++st) {
;                     u32x4 w;
;                     w.x = pk_bf16(x[kb][8 * st], x[kb][8 * st + 1]); w.y = pk_bf16(x[kb][8 * st + 2], x[kb][8 * st + 3]);
;                     w.z = pk_bf16(x[kb][8 * st + 4], x[kb][8 * st + 5]); w.w = pk_bf16(x[kb][8 * st + 6], x[kb][8 * st + 7]);
;                     const bf16x8 pfr = __builtin_bit_cast(bf16x8, w);
; #pragma unroll
;                     for (int d = 0; d < 2; ++d) {
;                         const bf16_t* vp = vb_ + (32 * d + r) * 68 + 32 * kb + 16 * st + 4 * h;
;                         const s16x4 lo = *(const s16x4*)vp, hi = *(const s16x4*)(vp + 8);
;                         const bf16x8 vf = __builtin_shufflevector(lo, hi, 0, 1, 2, 3, 4, 5, 6, 7);
;                         O[s][d] = MFMA32(vf, pfr, O[s][d]);
;                     }
;                 }
;         }
;         if (kt + 1 < nkt) {
;             bf16_t* wk = sK + (cur ^ 1) * 64 * 72; bf16_t* wv = sV + (cur ^ 1) * 64 * 68;
; #pragma unroll
;             for (int i = 0; i < 2; ++i) {
;                 *(u32x4*)(wk + (srow + 32 * i) * 72 + sc8) = rk[i];
;                 *(u32x2*)(wv + (srow + 32 * i) * 68 + sc8) = (u32x2){rv[i].x, rv[i].y}; *(u32x2*)(wv + (srow + 32 * i) * 68 + sc8 + 4) = (u32x2){rv[i].z, rv[i].w};
;             }
;         }
	v_pk_add_f32 v[88:89], v[88:89], v[152:153] neg_lo:[0,1] neg_hi:[0,1]
	v_pk_add_f32 v[90:91], v[90:91], v[152:153] neg_lo:[0,1] neg_hi:[0,1]
	v_pk_add_f32 v[92:93], v[92:93], v[152:153] neg_lo:[0,1] neg_hi:[0,1]
	v_pk_add_f32 v[94:95], v[94:95], v[152:153] neg_lo:[0,1] neg_hi:[0,1]
	v_mfma_f32_32x32x16_bf16 v[32:47], v[96:99], v[80:83], v[32:47]
	v_mfma_f32_32x32x16_bf16 v[0:15], v[112:115], v[80:83], v[0:15]
	v_exp_f32_e32 v88, v88
	v_exp_f32_e32 v89, v89
	v_exp_f32_e32 v90, v90
	v_exp_f32_e32 v91, v91
	v_exp_f32_e32 v92, v92
	v_exp_f32_e32 v93, v93
	v_exp_f32_e32 v94, v94
	v_exp_f32_e32 v95, v95
	v_add_f32_e32 v211, v211, v88
	v_add_f32_e32 v212, v212, v89
	v_add_f32_e32 v211, v211, v90
	v_add_f32_e32 v212, v212, v91
	v_add_f32_e32 v211, v211, v92
	v_add_f32_e32 v212, v212, v93
	v_add_f32_e32 v211, v211, v94
	v_add_f32_e32 v212, v212, v95
	v_cvt_pk_bf16_f32 v88, v88, v89
	v_cvt_pk_bf16_f32 v89, v90, v91
	v_cvt_pk_bf16_f32 v90, v92, v93
	v_cvt_pk_bf16_f32 v91, v94, v95
	v_pk_add_f32 v[64:65], v[64:65], v[152:153] neg_lo:[0,1] neg_hi:[0,1]
	v_pk_add_f32 v[66:67], v[66:67], v[152:153] neg_lo:[0,1] neg_hi:[0,1]
	v_pk_add_f32 v[68:69], v[68:69], v[152:153] neg_lo:[0,1] neg_hi:[0,1]
	v_pk_add_f32 v[70:71], v[70:71], v[152:153] neg_lo:[0,1] neg_hi:[0,1]
	v_mfma_f32_32x32x16_bf16 v[32:47], v[100:103], v[88:91], v[32:47]
	v_mfma_f32_32x32x16_bf16 v[0:15], v[116:119], v[88:91], v[0:15]
	v_mfma_f32_32x32x16_bf16 v[80:95], v[174:177], v[224:227], 0
	v_mfma_f32_32x32x16_bf16 v[80:95], v[182:185], v[240:243], v[80:95]
	v_exp_f32_e32 v64, v64
	v_exp_f32_e32 v65, v65
	v_exp_f32_e32 v66, v66
	v_exp_f32_e32 v67, v67
	v_exp_f32_e32 v68, v68
	v_exp_f32_e32 v69, v69
	v_exp_f32_e32 v70, v70
	v_exp_f32_e32 v71, v71
	v_add_f32_e32 v211, v211, v64
	v_add_f32_e32 v212, v212, v65
	v_add_f32_e32 v211, v211, v66
	v_add_f32_e32 v212, v212, v67
	v_add_f32_e32 v211, v211, v68
	v_add_f32_e32 v212, v212, v69
	v_add_f32_e32 v211, v211, v70
	v_add_f32_e32 v212, v212, v71
	v_cvt_pk_bf16_f32 v64, v64, v65
	v_cvt_pk_bf16_f32 v65, v66, v67
	v_cvt_pk_bf16_f32 v66, v68, v69
	v_cvt_pk_bf16_f32 v67, v70, v71
	v_pk_add_f32 v[72:73], v[72:73], v[152:153] neg_lo:[0,1] neg_hi:[0,1]
	v_pk_add_f32 v[74:75], v[74:75], v[152:153] neg_lo:[0,1] neg_hi:[0,1]
	v_pk_add_f32 v[76:77], v[76:77], v[152:153] neg_lo:[0,1] neg_hi:[0,1]
	v_pk_add_f32 v[78:79], v[78:79], v[152:153] neg_lo:[0,1] neg_hi:[0,1]
	v_mfma_f32_32x32x16_bf16 v[32:47], v[104:107], v[64:67], v[32:47]
	v_mfma_f32_32x32x16_bf16 v[0:15], v[120:123], v[64:67], v[0:15]
	v_exp_f32_e32 v72, v72
	v_exp_f32_e32 v73, v73
	v_exp_f32_e32 v74, v74
	v_exp_f32_e32 v75, v75
	v_exp_f32_e32 v76, v76
	v_exp_f32_e32 v77, v77
	v_exp_f32_e32 v78, v78
	v_exp_f32_e32 v79, v79
	v_add_f32_e32 v211, v211, v72
	v_add_f32_e32 v212, v212, v73
	v_add_f32_e32 v211, v211, v74
	v_add_f32_e32 v212, v212, v75
	v_add_f32_e32 v211, v211, v76
	v_add_f32_e32 v212, v212, v77
	v_add_f32_e32 v211, v211, v78
	v_add_f32_e32 v212, v212, v79
	v_cvt_pk_bf16_f32 v72, v72, v73
	v_cvt_pk_bf16_f32 v73, v74, v75
	v_cvt_pk_bf16_f32 v74, v76, v77
	v_cvt_pk_bf16_f32 v75, v78, v79
	v_add_f32_e32 v211, v211, v212
	v_add_f32_e32 v151, v151, v211
	v_mfma_f32_32x32x16_bf16 v[32:47], v[108:111], v[72:75], v[32:47]
	v_mfma_f32_32x32x16_bf16 v[0:15], v[124:127], v[72:75], v[0:15]
	v_mfma_f32_32x32x16_bf16 v[64:79], v[178:181], v[224:227], 0
	v_mfma_f32_32x32x16_bf16 v[64:79], v[186:189], v[240:243], v[64:79]
	s_xor_b32 s9, s9, 1
	s_mul_i32 s10, s9, 0x2400
	s_mul_i32 s11, s9, 0x2200
	v_add_u32_e32 v214, s10, v148
	v_add_u32_e32 v215, s11, v150
	v_add_u32_e32 v213, 0x5900, v215
	v_add_u32_e32 v215, 0x4800, v215
	v_add_u32_e32 v206, s10, v149
	s_waitcnt vmcnt(0)
	ds_write_b128 v214, v[190:193]
	ds_write_b128 v214, v[194:197] offset:4608
	ds_write2_b64 v215, v[198:199], v[200:201] offset1:1
	ds_write2_b64 v213, v[202:203], v[204:205] offset1:1
	s_cmp_lt_u32 s8, 0x82
	s_cbranch_scc0 .Lat32_skipld
	s_mov_b64 s[10:11], 0x80
	v_lshl_add_u64 v[244:245], v[244:245], 0, s[10:11]
	v_lshl_add_u64 v[246:247], v[246:247], 0, s[10:11]
	s_mov_b64 s[10:11], 0x2000
	v_lshl_add_u64 v[248:249], v[248:249], 0, s[10:11]
	global_load_dwordx4 v[190:193], v[248:249], off offset:-4096
	global_load_dwordx4 v[194:197], v[248:249], off
	global_load_dwordx4 v[198:201], v[244:245], off offset:128
	global_load_dwordx4 v[202:205], v[246:247], off offset:128
; template <int DK>
; DI void attn_item(const Params& p, int layer, int b, int hd, int qt, int ctxq, char* smem) {
;     ...
;             float mx = x[0][0];
; #pragma unroll
;             for (int i = 1; i < 16; ++i) mx = fmaxf(mx, x[0][i]);
; #pragma unroll
;             for (int i = 0; i < 16; ++i) mx = fmaxf(mx, x[1][i]);
;             mx = fmaxf(mx, shx(mx, lane, 32));
;             if (__builtin_amdgcn_ballot_w64(mx > m_[s] + 8.f) != 0) {
;                 const float mn = fmaxf(m_[s], mx);
;                 const float al = __builtin_amdgcn_exp2f(m_[s] - mn);
;                 m_[s] = mn;
;                 l_[s] *= al;
; #pragma unroll
;                 for (int d = 0; d < 2; ++d)
; #pragma unroll
;                     for (int i = 0; i < 16; ++i) O[s][d][i] *= al;
;             }
;             const f32x2 mref = {m_[s], m_[s]};
;             float ps = 0.f;
; #pragma unroll
;             for (int kb = 0; kb < 2; ++kb)
; #pragma unroll
;                 for (int i2 = 0; i2 < 8; ++i2) {
;                     f32x2 t = {x[kb][2 * i2], x[kb][2 * i2 + 1]};
;                     asm("v_pk_add_f32 %0, %1, %2 neg_lo:[0,1] neg_hi:[0,1]" : "=v"(t) : "v"(t), "v"(mref));
;                     const float e0 = __builtin_amdgcn_exp2f(t.x), e1 = __builtin_amdgcn_exp2f(t.y);
;                     x[kb][2 * i2] = e0; x[kb][2 * i2 + 1] = e1; ps += e0 + e1;
;                 }
;             l_[s] += ps;
; #pragma unroll
;             for (int kb = 0; kb < 2; ++kb)
; #pragma unroll
;                 for (int st = 0; st < 2; ++st) {
;                     u32x4 w;
;                     w.x = pk_bf16(x[kb][8 * st], x[kb][8 * st + 1]); w.y = pk_bf16(x[kb][8 * st + 2], x[kb][8 * st + 3]);
;                     w.z = pk_bf16(x[kb][8 * st + 4], x[kb][8 * st + 5]); w.w = pk_bf16(x[kb][8 * st + 6], x[kb][8 * st + 7]);
;                     const bf16x8 pfr = __builtin_bit_cast(bf16x8, w);
; #pragma unroll
;                     for (int d = 0; d < 2; ++d) {
;                         const bf16_t* vp = vb_ + (32 * d + r) * 68 + 32 * kb + 16 * st + 4 * h;
;                         const s16x4 lo = *(const s16x4*)vp, hi = *(const s16x4*)(vp + 8);
;                         const bf16x8 vf = __builtin_shufflevector(lo, hi, 0, 1, 2, 3, 4, 5, 6, 7);
;                         O[s][d] = MFMA32(vf, pfr, O[s][d]);
;                     }
;                 }
;         }
;         if (kt + 1 < nkt) {
.Lat32_skipld:
	v_max3_f32 v209, v80, v81, v82
	v_max3_f32 v209, v209, v83, v84
	v_max3_f32 v209, v209, v85, v86
	v_max3_f32 v209, v209, v87, v88
	v_max3_f32 v209, v209, v89, v90
	v_max3_f32 v209, v209, v91, v92
	v_max3_f32 v209, v209, v93, v94
	v_max3_f32 v209, v209, v95, v64
	v_max3_f32 v209, v209, v65, v66
	v_max3_f32 v209, v209, v67, v68
	v_max3_f32 v209, v209, v69, v70
	v_max3_f32 v209, v209, v71, v72
	v_max3_f32 v209, v209, v73, v74
	v_max3_f32 v209, v209, v75, v76
	v_max3_f32 v209, v209, v77, v78
	v_max_f32_e32 v209, v209, v79
	v_mov_b32_e32 v210, v209
	s_nop 1
	v_permlane32_swap_b32_e32 v210, v209
	s_nop 0
	v_max_f32_e32 v209, v209, v210
	v_add_f32_e32 v210, 0x41000000, v146
	v_cmp_gt_f32_e32 vcc, v209, v210
	s_cbranch_vccz .Lat32_nors1
	v_max_f32_e32 v213, v146, v209
	v_sub_f32_e32 v210, v146, v213
	v_exp_f32_e32 v210, v210
	v_mov_b32_e32 v146, v213
	v_mov_b32_e32 v147, v213
	v_mul_f32_e32 v170, v170, v210
	v_pk_mul_f32 v[48:49], v[48:49], v[210:211] op_sel_hi:[1,0]
	v_pk_mul_f32 v[50:51], v[50:51], v[210:211] op_sel_hi:[1,0]
	v_pk_mul_f32 v[52:53], v[52:53], v[210:211] op_sel_hi:[1,0]
	v_pk_mul_f32 v[54:55], v[54:55], v[210:211] op_sel_hi:[1,0]
	v_pk_mul_f32 v[56:57], v[56:57], v[210:211] op_sel_hi:[1,0]
	v_pk_mul_f32 v[58:59], v[58:59], v[210:211] op_sel_hi:[1,0]
	v_pk_mul_f32 v[60:61], v[60:61], v[210:211] op_sel_hi:[1,0]
	v_pk_mul_f32 v[62:63], v[62:63], v[210:211] op_sel_hi:[1,0]
	v_pk_mul_f32 v[16:17], v[16:17], v[210:211] op_sel_hi:[1,0]
	v_pk_mul_f32 v[18:19], v[18:19], v[210:211] op_sel_hi:[1,0]
	v_pk_mul_f32 v[20:21], v[20:21], v[210:211] op_sel_hi:[1,0]
	v_pk_mul_f32 v[22:23], v[22:23], v[210:211] op_sel_hi:[1,0]
	v_pk_mul_f32 v[24:25], v[24:25], v[210:211] op_sel_hi:[1,0]
	v_pk_mul_f32 v[26:27], v[26:27], v[210:211] op_sel_hi:[1,0]
	v_pk_mul_f32 v[28:29], v[28:29], v[210:211] op_sel_hi:[1,0]
	v_pk_mul_f32 v[30:31], v[30:31], v[210:211] op_sel_hi:[1,0]
.Lat32_nors1:
	v_pk_add_f32 v[80:81], v[80:81], v[146:147] neg_lo:[0,1] neg_hi:[0,1]
	v_pk_add_f32 v[82:83], v[82:83], v[146:147] neg_lo:[0,1] neg_hi:[0,1]
	v_pk_add_f32 v[84:85], v[84:85], v[146:147] neg_lo:[0,1] neg_hi:[0,1]
	v_pk_add_f32 v[86:87], v[86:87], v[146:147] neg_lo:[0,1] neg_hi:[0,1]
	v_exp_f32_e32 v80, v80
	v_exp_f32_e32 v81, v81
	v_exp_f32_e32 v82, v82
	v_exp_f32_e32 v83, v83
	v_exp_f32_e32 v84, v84
	v_exp_f32_e32 v85, v85
	v_exp_f32_e32 v86, v86
	v_exp_f32_e32 v87, v87
	v_add_f32_e32 v211, v80, v82
	v_add_f32_e32 v212, v81, v83
	v_add_f32_e32 v211, v211, v84
	v_add_f32_e32 v212, v212, v85
	v_add_f32_e32 v211, v211, v86
	v_add_f32_e32 v212, v212, v87
	v_cvt_pk_bf16_f32 v80, v80, v81
	v_cvt_pk_bf16_f32 v81, v82, v83
	v_cvt_pk_bf16_f32 v82, v84, v85
	v_cvt_pk_bf16_f32 v83, v86, v87
	v_pk_add_f32 v[88:89], v[88:89], v[146:147] neg_lo:[0,1] neg_hi:[0,1]
	v_pk_add_f32 v[90:91], v[90:91], v[146:147] neg_lo:[0,1] neg_hi:[0,1]
	v_pk_add_f32 v[92:93], v[92:93], v[146:147] neg_lo:[0,1] neg_hi:[0,1]
	v_pk_add_f32 v[94:95], v[94:95], v[146:147] neg_lo:[0,1] neg_hi:[0,1]
	v_mfma_f32_32x32x16_bf16 v[48:63], v[96:99], v[80:83], v[48:63]
	v_mfma_f32_32x32x16_bf16 v[16:31], v[112:115], v[80:83], v[16:31]
	v_exp_f32_e32 v88, v88
	v_exp_f32_e32 v89, v89
	v_exp_f32_e32 v90, v90
	v_exp_f32_e32 v91, v91
	v_exp_f32_e32 v92, v92
	v_exp_f32_e32 v93, v93
	v_exp_f32_e32 v94, v94
	v_exp_f32_e32 v95, v95
	v_add_f32_e32 v211, v211, v88
	v_add_f32_e32 v212, v212, v89
	v_add_f32_e32 v211, v211, v90
	v_add_f32_e32 v212, v212, v91
	v_add_f32_e32 v211, v211, v92
	v_add_f32_e32 v212, v212, v93
	v_add_f32_e32 v211, v211, v94
	v_add_f32_e32 v212, v212, v95
	v_cvt_pk_bf16_f32 v88, v88, v89
	v_cvt_pk_bf16_f32 v89, v90, v91
	v_cvt_pk_bf16_f32 v90, v92, v93
	v_cvt_pk_bf16_f32 v91, v94, v95
	v_pk_add_f32 v[64:65], v[64:65], v[146:147] neg_lo:[0,1] neg_hi:[0,1]
	v_pk_add_f32 v[66:67], v[66:67], v[146:147] neg_lo:[0,1] neg_hi:[0,1]
	v_pk_add_f32 v[68:69], v[68:69], v[146:147] neg_lo:[0,1] neg_hi:[0,1]
	v_pk_add_f32 v[70:71], v[70:71], v[146:147] neg_lo:[0,1] neg_hi:[0,1]
	v_mfma_f32_32x32x16_bf16 v[48:63], v[100:103], v[88:91], v[48:63]
	v_mfma_f32_32x32x16_bf16 v[16:31], v[116:119], v[88:91], v[16:31]
	s_waitcnt lgkmcnt(0)
	s_barrier
	ds_read_b128 v[128:131], v206
	ds_read_b128 v[132:135], v206 offset:4608
	ds_read_b128 v[136:139], v206 offset:32
	ds_read_b128 v[140:143], v206 offset:4640
	v_exp_f32_e32 v64, v64
	v_exp_f32_e32 v65, v65
	v_exp_f32_e32 v66, v66
	v_exp_f32_e32 v67, v67
	v_exp_f32_e32 v68, v68
	v_exp_f32_e32 v69, v69
	v_exp_f32_e32 v70, v70
	v_exp_f32_e32 v71, v71
	v_add_f32_e32 v211, v211, v64
	v_add_f32_e32 v212, v212, v65
	v_add_f32_e32 v211, v211, v66
	v_add_f32_e32 v212, v212, v67
	v_add_f32_e32 v211, v211, v68
	v_add_f32_e32 v212, v212, v69
	v_add_f32_e32 v211, v211, v70
	v_add_f32_e32 v212, v212, v71
	v_cvt_pk_bf16_f32 v64, v64, v65
	v_cvt_pk_bf16_f32 v65, v66, v67
	v_cvt_pk_bf16_f32 v66, v68, v69
	v_cvt_pk_bf16_f32 v67, v70, v71
	v_pk_add_f32 v[72:73], v[72:73], v[146:147] neg_lo:[0,1] neg_hi:[0,1]
	v_pk_add_f32 v[74:75], v[74:75], v[146:147] neg_lo:[0,1] neg_hi:[0,1]
	v_pk_add_f32 v[76:77], v[76:77], v[146:147] neg_lo:[0,1] neg_hi:[0,1]
	v_pk_add_f32 v[78:79], v[78:79], v[146:147] neg_lo:[0,1] neg_hi:[0,1]
	v_mfma_f32_32x32x16_bf16 v[48:63], v[104:107], v[64:67], v[48:63]
	v_mfma_f32_32x32x16_bf16 v[16:31], v[120:123], v[64:67], v[16:31]
	v_exp_f32_e32 v72, v72
	v_exp_f32_e32 v73, v73
	v_exp_f32_e32 v74, v74
	v_exp_f32_e32 v75, v75
	v_exp_f32_e32 v76, v76
	v_exp_f32_e32 v77, v77
	v_exp_f32_e32 v78, v78
	v_exp_f32_e32 v79, v79
	v_add_f32_e32 v211, v211, v72
	v_add_f32_e32 v212, v212, v73
	v_add_f32_e32 v211, v211, v74
	v_add_f32_e32 v212, v212, v75
	v_add_f32_e32 v211, v211, v76
	v_add_f32_e32 v212, v212, v77
	v_add_f32_e32 v211, v211, v78
	v_add_f32_e32 v212, v212, v79
	v_cvt_pk_bf16_f32 v72, v72, v73
	v_cvt_pk_bf16_f32 v73, v74, v75
	v_cvt_pk_bf16_f32 v74, v76, v77
	v_cvt_pk_bf16_f32 v75, v78, v79
	v_add_f32_e32 v211, v211, v212
	v_add_f32_e32 v170, v170, v211
	v_mfma_f32_32x32x16_bf16 v[48:63], v[108:111], v[72:75], v[48:63]
	v_mfma_f32_32x32x16_bf16 v[16:31], v[124:127], v[72:75], v[16:31]
	s_add_i32 s8, s8, 1
	s_cmpk_eq_i32 s8, 0x83
	s_cbranch_scc0 .Lat32_loop
	s_waitcnt lgkmcnt(0)
